# lever 4 variant: static s_setprio 3 (instead of 1) for blocks >= grid/2
# baseline (speedup 1.0000x reference)
; #define LAS __attribute__((address_space(3)))
; __global__ void __launch_bounds__(256, 2) fwd_megakernel(Params p) {
;   cg::grid_group grid = cg::this_grid();
;   __shared__ __attribute__((aligned(16))) unsigned char smem[SMEM_BYTES];
;   unsigned char* ws = p.ws;
;   __shared__ __attribute__((aligned(16))) unsigned xb_words[4];
;   if (threadIdx.x < 4) xb_words[threadIdx.x] = 0u;
;   __syncthreads();
;   XcdBarrier gbar = xcd_barrier_post((unsigned*)(ws + OFF_BAR), (volatile LAS unsigned*)&xb_words);
_Z14fwd_megakernel6Params:
	v_and_b32_e32 v160, 0x3ff, v0
	v_writelane_b32 v255, s2, 0
	v_cmp_gt_u32_e32 vcc, 4, v160
	s_nop 0
	v_writelane_b32 v255, s3, 1
	s_mov_b64 s[2:3], s[0:1]
	s_load_dword s0, s[0:1], 0x210
	s_nop 0
	s_load_dwordx2 s[26:27], s[2:3], 0x208
	s_load_dwordx2 s[22:23], s[2:3], 0x80
	s_add_u32 s8, s2, 0x208
	s_addc_u32 s9, s3, 0
	s_waitcnt lgkmcnt(0)
	v_readlane_b32 s98, v255, 0
	s_lshr_b32 s99, s26, 1
	s_cmp_ge_u32 s98, s99
	s_cbranch_scc0 .Lmy_sprio
	s_setprio 3
